# phase A weight transposes software-pipelined: next job's 8 loads issued before the previous job's LDS-read/convert/store half; on top of v54
# speedup vs baseline: 1.0055x; 1.0055x over previous
.LBB0_22:
	v_readlane_b32 s0, v252, 0
	s_cmpk_gt_i32 s0, 0x87f
	s_cbranch_scc1 .LBB0_46
	v_ashrrev_i32_e32 v5, 3, v16
	v_lshlrev_b32_e32 v3, 2, v5
	v_and_b32_e32 v6, 0x80, v3
	v_and_b32_e32 v7, 16, v5
	v_ashrrev_i32_e32 v4, 4, v16
	v_add3_u32 v6, 0, v6, v7
	v_and_b32_e32 v3, 12, v3
	v_and_b32_e32 v7, 0x60, v16
	s_movk_i32 s0, 0x104
	v_add3_u32 v21, v6, v3, v7
	v_mul_lo_u32 v3, v4, s0
	s_add_u32 s0, s58, 0xc00000
	s_addc_u32 s1, s59, 0
	s_add_u32 s4, s58, 0x800000
	s_addc_u32 s5, s59, 0
	s_add_u32 s6, s58, 0x400000
	v_lshlrev_b32_e32 v2, 3, v16
	s_addc_u32 s7, s59, 0
	v_and_b32_e32 v0, 60, v17
	v_and_b32_e32 v2, 56, v2
	s_add_u32 s8, s58, 0x1400000
	v_mul_u32_u24_e32 v22, 0x104, v2
	v_lshlrev_b32_e32 v6, 2, v0
	s_addc_u32 s9, s59, 0
	v_mov_b32_e32 v1, 0
	v_add3_u32 v6, 0, v3, v6
	s_add_u32 s10, s58, 0x2400000
	v_readlane_b32 s28, v252, 0
	v_add_u32_e32 v21, v21, v22
	s_addc_u32 s11, s59, 0
	s_lshl_b32 s2, s28, 3
	s_lshl_b32 s3, s96, 3
	s_lshl_b32 s24, s28, 4
	s_lshl_b32 s25, s96, 4
	s_lshl_b32 s26, s28, 2
	s_lshl_b32 s27, s96, 2
	v_lshlrev_b32_e32 v0, 2, v0
	v_add_u32_e32 v7, 0x2080, v6
	v_add_u32_e32 v8, 0x2088, v6
	v_add_u32_e32 v9, 0x4100, v6
	v_add_u32_e32 v10, 0x4108, v6
	v_add_u32_e32 v11, 0x6180, v6
	v_add_u32_e32 v12, 0x6188, v6
	v_add_u32_e32 v13, 0x8200, v6
	v_add_u32_e32 v14, 0x8208, v6
	v_add_u32_e32 v15, 0xa280, v6
	v_add_u32_e32 v16, 0xa288, v6
	v_add_u32_e32 v17, 0xc300, v6
	v_add_u32_e32 v18, 0xc308, v6
	v_add_u32_e32 v19, 0xe380, v6
	v_add_u32_e32 v20, 0xe388, v6
	v_lshlrev_b32_e32 v2, 1, v2
	v_mov_b32_e32 v3, v1
	v_add_u32_e32 v22, 0x400, v21
	v_add_u32_e32 v23, 0x4000, v21
	v_add_u32_e32 v24, 0x4200, v21
	v_add_u32_e32 v25, 0x4400, v21
	v_add_u32_e32 v26, 0x4600, v21
	v_add_u32_e32 v27, 0x8000, v21
	v_add_u32_e32 v28, 0x8400, v21
	v_add_u32_e32 v29, 0x8800, v21
	v_add_u32_e32 v30, 0xc200, v21
	v_add_u32_e32 v31, 0xc400, v21
	v_add_u32_e32 v32, 0xc600, v21
	v_add_u32_e32 v33, 0xc800, v21
	s_mov_b32 s98, 0
	s_branch .LBB0_26

.LBB0_25:
	v_mov_b64_e32 v[132:133], v[66:67]
	s_lshl_b32 s20, s17, 6
	v_add_u32_e32 v34, s20, v4
	v_ashrrev_i32_e32 v35, 31, v34
	v_mul_lo_u32 v36, s22, v35
	v_mul_lo_u32 v37, s23, v34
	v_mad_u64_u32 v[34:35], s[30:31], s22, v34, 0
	v_add3_u32 v35, v35, v36, v37
	v_lshl_add_u64 v[34:35], v[34:35], 2, s[18:19]
	s_ashr_i32 s17, s16, 31
	v_lshl_add_u64 v[34:35], s[16:17], 2, v[34:35]
	v_lshl_add_u64 v[38:39], v[34:35], 0, v[0:1]
	s_waitcnt lgkmcnt(0)
	global_load_dwordx4 v[34:37], v[38:39], off nt
	s_lshl_b64 s[16:17], s[22:23], 7
	v_lshl_add_u64 v[42:43], v[38:39], 0, s[16:17]
	global_load_dwordx4 v[38:41], v[42:43], off nt
	v_lshl_add_u64 v[46:47], v[42:43], 0, s[16:17]
	global_load_dwordx4 v[42:45], v[46:47], off nt
	v_lshl_add_u64 v[50:51], v[46:47], 0, s[16:17]
	global_load_dwordx4 v[46:49], v[50:51], off nt
	v_lshl_add_u64 v[54:55], v[50:51], 0, s[16:17]
	global_load_dwordx4 v[50:53], v[54:55], off nt
	v_lshl_add_u64 v[58:59], v[54:55], 0, s[16:17]
	global_load_dwordx4 v[54:57], v[58:59], off nt
	v_lshl_add_u64 v[62:63], v[58:59], 0, s[16:17]
	global_load_dwordx4 v[58:61], v[62:63], off nt
	v_lshl_add_u64 v[62:63], v[62:63], 0, s[16:17]
	global_load_dwordx4 v[62:65], v[62:63], off nt
	v_add_u32_e32 v66, s29, v5
	v_ashrrev_i32_e32 v68, 31, v66
	v_mul_lo_u32 v69, s13, v66
	v_mad_u64_u32 v[66:67], s[16:17], s12, v66, 0
	v_mul_lo_u32 v68, s12, v68
	v_add3_u32 v67, v67, v68, v69
	v_lshl_add_u64 v[66:67], v[66:67], 1, s[14:15]
	s_add_i32 s28, s28, s96
	s_add_i32 s2, s2, s3
	s_add_i32 s24, s24, s25
	s_add_i32 s26, s26, s27
	s_ashr_i32 s21, s20, 31
	v_lshl_add_u64 v[66:67], v[66:67], 0, v[2:3]
	s_cmpk_lt_i32 s28, 0x880
	v_lshl_add_u64 v[66:67], s[20:21], 1, v[66:67]
	s_cselect_b32 s99, 1, 0
	s_cmp_eq_u32 s98, 0
	s_cbranch_scc1 .Ltr_first
	ds_read2_b32 v[100:101], v21 offset1:65
	ds_read2_b32 v[102:103], v21 offset0:130 offset1:195
	ds_read2_b32 v[104:105], v22 offset0:4 offset1:69
	ds_read2_b32 v[106:107], v22 offset0:134 offset1:199
	ds_read2_b32 v[108:109], v23 offset0:64 offset1:129
	ds_read2_b32 v[110:111], v24 offset0:66 offset1:131
	ds_read2_b32 v[112:113], v25 offset0:68 offset1:133
	ds_read2_b32 v[114:115], v26 offset0:70 offset1:135
	ds_read2_b32 v[116:117], v27 offset0:128 offset1:193
	ds_read2_b32 v[118:119], v28 offset0:2 offset1:67
	ds_read2_b32 v[120:121], v28 offset0:132 offset1:197
	ds_read2_b32 v[122:123], v29 offset0:6 offset1:71
	ds_read2_b32 v[124:125], v30 offset0:64 offset1:129
	ds_read2_b32 v[126:127], v31 offset0:66 offset1:131
	ds_read2_b32 v[128:129], v32 offset0:68 offset1:133
	ds_read2_b32 v[130:131], v33 offset0:70 offset1:135
	s_waitcnt lgkmcnt(14)
	v_cvt_pk_bf16_f32 v100, v100, v101
	v_cvt_pk_bf16_f32 v101, v102, v103
	s_waitcnt lgkmcnt(13)
	v_cvt_pk_bf16_f32 v102, v104, v105
	s_waitcnt lgkmcnt(12)
	v_cvt_pk_bf16_f32 v103, v106, v107
	s_waitcnt lgkmcnt(11)
	v_cvt_pk_bf16_f32 v104, v108, v109
	s_waitcnt lgkmcnt(10)
	v_cvt_pk_bf16_f32 v105, v110, v111
	s_waitcnt lgkmcnt(9)
	v_cvt_pk_bf16_f32 v106, v112, v113
	s_waitcnt lgkmcnt(8)
	v_cvt_pk_bf16_f32 v107, v114, v115
	s_waitcnt lgkmcnt(7)
	v_cvt_pk_bf16_f32 v108, v116, v117
	s_waitcnt lgkmcnt(6)
	v_cvt_pk_bf16_f32 v109, v118, v119
	s_waitcnt lgkmcnt(5)
	v_cvt_pk_bf16_f32 v110, v120, v121
	s_waitcnt lgkmcnt(4)
	v_cvt_pk_bf16_f32 v111, v122, v123
	s_waitcnt lgkmcnt(3)
	v_cvt_pk_bf16_f32 v112, v124, v125
	s_waitcnt lgkmcnt(2)
	v_cvt_pk_bf16_f32 v113, v126, v127
	s_waitcnt lgkmcnt(1)
	v_cvt_pk_bf16_f32 v114, v128, v129
	s_waitcnt lgkmcnt(0)
	v_cvt_pk_bf16_f32 v115, v130, v131
	global_store_dwordx4 v[132:133], v[100:103], off
	global_store_dwordx4 v[132:133], v[104:107], off offset:128
	global_store_dwordx4 v[132:133], v[108:111], off offset:256
	global_store_dwordx4 v[132:133], v[112:115], off offset:384
	s_barrier
	s_waitcnt vmcnt(11)
	ds_write2_b32 v6, v34, v35 offset1:1
	ds_write2_b32 v6, v36, v37 offset0:2 offset1:3
	s_waitcnt vmcnt(10)
	ds_write2_b32 v7, v38, v39 offset1:1
	ds_write2_b32 v8, v40, v41 offset1:1
	s_waitcnt vmcnt(9)
	ds_write2_b32 v9, v42, v43 offset1:1
	ds_write2_b32 v10, v44, v45 offset1:1
	s_waitcnt vmcnt(8)
	ds_write2_b32 v11, v46, v47 offset1:1
	ds_write2_b32 v12, v48, v49 offset1:1
	s_waitcnt vmcnt(7)
	ds_write2_b32 v13, v50, v51 offset1:1
	ds_write2_b32 v14, v52, v53 offset1:1
	s_waitcnt vmcnt(6)
	ds_write2_b32 v15, v54, v55 offset1:1
	ds_write2_b32 v16, v56, v57 offset1:1
	s_waitcnt vmcnt(5)
	ds_write2_b32 v17, v58, v59 offset1:1
	ds_write2_b32 v18, v60, v61 offset1:1
	s_waitcnt vmcnt(4)
	ds_write2_b32 v19, v62, v63 offset1:1
	ds_write2_b32 v20, v64, v65 offset1:1
	s_waitcnt lgkmcnt(0)
	s_branch .Ltr_join
.Ltr_first:
	s_barrier
	s_waitcnt vmcnt(7)
	ds_write2_b32 v6, v34, v35 offset1:1
	ds_write2_b32 v6, v36, v37 offset0:2 offset1:3
	s_waitcnt vmcnt(6)
	ds_write2_b32 v7, v38, v39 offset1:1
	ds_write2_b32 v8, v40, v41 offset1:1
	s_waitcnt vmcnt(5)
	ds_write2_b32 v9, v42, v43 offset1:1
	ds_write2_b32 v10, v44, v45 offset1:1
	s_waitcnt vmcnt(4)
	ds_write2_b32 v11, v46, v47 offset1:1
	ds_write2_b32 v12, v48, v49 offset1:1
	s_waitcnt vmcnt(3)
	ds_write2_b32 v13, v50, v51 offset1:1
	ds_write2_b32 v14, v52, v53 offset1:1
	s_waitcnt vmcnt(2)
	ds_write2_b32 v15, v54, v55 offset1:1
	ds_write2_b32 v16, v56, v57 offset1:1
	s_waitcnt vmcnt(1)
	ds_write2_b32 v17, v58, v59 offset1:1
	ds_write2_b32 v18, v60, v61 offset1:1
	s_waitcnt vmcnt(0)
	ds_write2_b32 v19, v62, v63 offset1:1
	ds_write2_b32 v20, v64, v65 offset1:1
	s_waitcnt lgkmcnt(0)
.Ltr_join:
	s_barrier
	s_mov_b32 s98, 1
	s_cmp_eq_u32 s99, 1
	s_cbranch_scc1 .LBB0_26
	v_mov_b64_e32 v[132:133], v[66:67]
	ds_read2_b32 v[100:101], v21 offset1:65
	ds_read2_b32 v[102:103], v21 offset0:130 offset1:195
	ds_read2_b32 v[104:105], v22 offset0:4 offset1:69
	ds_read2_b32 v[106:107], v22 offset0:134 offset1:199
	ds_read2_b32 v[108:109], v23 offset0:64 offset1:129
	ds_read2_b32 v[110:111], v24 offset0:66 offset1:131
	ds_read2_b32 v[112:113], v25 offset0:68 offset1:133
	ds_read2_b32 v[114:115], v26 offset0:70 offset1:135
	ds_read2_b32 v[116:117], v27 offset0:128 offset1:193
	ds_read2_b32 v[118:119], v28 offset0:2 offset1:67
	ds_read2_b32 v[120:121], v28 offset0:132 offset1:197
	ds_read2_b32 v[122:123], v29 offset0:6 offset1:71
	ds_read2_b32 v[124:125], v30 offset0:64 offset1:129
	ds_read2_b32 v[126:127], v31 offset0:66 offset1:131
	ds_read2_b32 v[128:129], v32 offset0:68 offset1:133
	ds_read2_b32 v[130:131], v33 offset0:70 offset1:135
	s_waitcnt lgkmcnt(14)
	v_cvt_pk_bf16_f32 v100, v100, v101
	v_cvt_pk_bf16_f32 v101, v102, v103
	s_waitcnt lgkmcnt(13)
	v_cvt_pk_bf16_f32 v102, v104, v105
	s_waitcnt lgkmcnt(12)
	v_cvt_pk_bf16_f32 v103, v106, v107
	s_waitcnt lgkmcnt(11)
	v_cvt_pk_bf16_f32 v104, v108, v109
	s_waitcnt lgkmcnt(10)
	v_cvt_pk_bf16_f32 v105, v110, v111
	s_waitcnt lgkmcnt(9)
	v_cvt_pk_bf16_f32 v106, v112, v113
	s_waitcnt lgkmcnt(8)
	v_cvt_pk_bf16_f32 v107, v114, v115
	s_waitcnt lgkmcnt(7)
	v_cvt_pk_bf16_f32 v108, v116, v117
	s_waitcnt lgkmcnt(6)
	v_cvt_pk_bf16_f32 v109, v118, v119
	s_waitcnt lgkmcnt(5)
	v_cvt_pk_bf16_f32 v110, v120, v121
	s_waitcnt lgkmcnt(4)
	v_cvt_pk_bf16_f32 v111, v122, v123
	s_waitcnt lgkmcnt(3)
	v_cvt_pk_bf16_f32 v112, v124, v125
	s_waitcnt lgkmcnt(2)
	v_cvt_pk_bf16_f32 v113, v126, v127
	s_waitcnt lgkmcnt(1)
	v_cvt_pk_bf16_f32 v114, v128, v129
	s_waitcnt lgkmcnt(0)
	v_cvt_pk_bf16_f32 v115, v130, v131
	global_store_dwordx4 v[132:133], v[100:103], off
	global_store_dwordx4 v[132:133], v[104:107], off offset:128
	global_store_dwordx4 v[132:133], v[108:111], off offset:256
	global_store_dwordx4 v[132:133], v[112:115], off offset:384
	s_branch .LBB0_46

.LBB0_44:
	s_andn2_b64 vcc, exec, s[12:13]
	s_cbranch_vccnz .LBB0_24
	s_add_i32 s16, s29, 0x400
	s_branch .LBB0_24
	s_nop 0
	s_nop 0
	s_nop 0
	s_nop 0
	s_nop 0
	s_nop 0
	s_nop 0
	s_nop 0
	s_nop 0
	s_nop 0
	s_nop 0
	s_nop 0
	s_nop 0
	s_nop 0
	s_nop 0
	s_nop 0
	s_nop 0
	s_nop 0
	s_nop 0
	s_nop 0
	s_nop 0
	s_nop 0
	s_nop 0
	s_nop 0
	s_nop 0
	s_nop 0
	s_nop 0
	s_nop 0
	s_nop 0
	s_nop 0
	s_nop 0
	s_nop 0
	s_nop 0
	s_nop 0
	s_nop 0
	s_nop 0
	s_nop 0
	s_nop 0
	s_nop 0
	s_nop 0
	s_nop 0
	s_nop 0
	s_nop 0
	s_nop 0
	s_nop 0
	s_nop 0
	s_nop 0
	s_nop 0
	s_nop 0
	s_nop 0
	s_nop 0
	s_nop 0
	s_nop 0
